# v109 + NA latent loop edge edit: softmax re-reference block moved out of line (common path falls through)
# baseline (speedup 1.0000x reference)
.LBB0_176:
	s_add_i32 s0, s10, -2
	s_and_b32 s16, s0, 1
	s_cmp_ge_i32 s0, s5
	s_mul_i32 s0, s16, 0x4600
	v_add_u32_e32 v14, s0, v146
	v_add_u32_e32 v0, s0, v147
	s_mov_b64 s[0:1], -1
	s_cbranch_scc0 .LBB0_180
	ds_read_b128 v[10:13], v14
	ds_read_b128 v[64:67], v14 offset:32
	s_mov_b32 s0, 0x47800000
	v_mov_b32_e32 v167, v151
	v_mov_b32_e32 v116, v15
	s_waitcnt lgkmcnt(1)
	v_mfma_f32_32x32x16_bf16 v[48:63], v[10:13], v[80:83], 0
	s_waitcnt lgkmcnt(0)
	v_mfma_f32_32x32x16_bf16 v[48:63], v[64:67], v[84:87], v[48:63]
	ds_read_b128 v[10:13], v14 offset:64
	ds_read_b128 v[64:67], v14 offset:96
	s_waitcnt lgkmcnt(1)
	v_mfma_f32_32x32x16_bf16 v[48:63], v[10:13], v[88:91], v[48:63]
	ds_read_b128 v[10:13], v14 offset:4608
	ds_read_b128 v[104:107], v14 offset:4640
	s_waitcnt lgkmcnt(2)
	v_mfma_f32_32x32x16_bf16 v[48:63], v[64:67], v[92:95], v[48:63]
	s_waitcnt lgkmcnt(1)
	v_mfma_f32_32x32x16_bf16 v[64:79], v[10:13], v[80:83], 0
	s_nop 9
	v_sub_f32_e32 v169, v48, v15
	v_sub_f32_e32 v171, v49, v15
	v_sub_f32_e32 v173, v50, v15
	v_sub_f32_e32 v175, v51, v15
	v_sub_f32_e32 v177, v52, v15
	v_sub_f32_e32 v179, v53, v15
	v_exp_f32_e32 v120, v177
	s_waitcnt lgkmcnt(0)
	v_mfma_f32_32x32x16_bf16 v[64:79], v[104:107], v[84:87], v[64:79]
	ds_read_b128 v[10:13], v14 offset:4672
	ds_read_b128 v[104:107], v14 offset:4704
	v_exp_f32_e32 v121, v179
	v_sub_f32_e32 v181, v54, v15
	v_sub_f32_e32 v183, v55, v15
	v_exp_f32_e32 v124, v181
	v_exp_f32_e32 v125, v183
	v_sub_f32_e32 v185, v56, v15
	s_waitcnt lgkmcnt(1)
	v_mfma_f32_32x32x16_bf16 v[64:79], v[10:13], v[88:91], v[64:79]
	v_exp_f32_e32 v12, v169
	v_exp_f32_e32 v13, v171
	v_sub_f32_e32 v187, v57, v15
	v_exp_f32_e32 v128, v185
	v_exp_f32_e32 v129, v187
	v_pk_add_f32 v[48:49], v[12:13], 0 op_sel_hi:[1,0]
	v_sub_f32_e32 v189, v58, v15
	s_waitcnt lgkmcnt(0)
	v_mfma_f32_32x32x16_bf16 v[64:79], v[104:107], v[92:95], v[64:79]
	v_exp_f32_e32 v106, v173
	v_exp_f32_e32 v107, v175
	v_sub_f32_e32 v191, v59, v15
	v_exp_f32_e32 v132, v189
	v_exp_f32_e32 v133, v191
	v_sub_f32_e32 v193, v60, v15
	v_sub_f32_e32 v195, v61, v15
	s_nop 4
	v_sub_f32_e32 v170, v64, v15
	v_sub_f32_e32 v172, v65, v15
	v_exp_f32_e32 v10, v170
	v_exp_f32_e32 v11, v172
	v_sub_f32_e32 v174, v66, v15
	v_sub_f32_e32 v176, v67, v15
	v_exp_f32_e32 v104, v174
	v_exp_f32_e32 v105, v176
	v_sub_f32_e32 v178, v68, v15
	v_sub_f32_e32 v180, v69, v15
	v_exp_f32_e32 v118, v178
	v_exp_f32_e32 v119, v180
	v_pk_add_f32 v[48:49], v[48:49], v[10:11]
	v_sub_f32_e32 v182, v70, v15
	v_sub_f32_e32 v184, v71, v15
	v_pk_add_f32 v[48:49], v[106:107], v[48:49]
	v_exp_f32_e32 v122, v182
	v_exp_f32_e32 v123, v184
	v_pk_add_f32 v[48:49], v[104:105], v[48:49]
	v_sub_f32_e32 v186, v72, v15
	v_sub_f32_e32 v188, v73, v15
	v_pk_add_f32 v[48:49], v[120:121], v[48:49]
	v_exp_f32_e32 v126, v186
	v_exp_f32_e32 v127, v188
	v_pk_add_f32 v[48:49], v[118:119], v[48:49]
	v_sub_f32_e32 v190, v74, v15
	v_sub_f32_e32 v192, v75, v15
	v_pk_add_f32 v[48:49], v[124:125], v[48:49]
	v_exp_f32_e32 v130, v190
	v_exp_f32_e32 v131, v192
	v_pk_add_f32 v[48:49], v[122:123], v[48:49]
	v_sub_f32_e32 v194, v76, v15
	v_sub_f32_e32 v196, v77, v15
	v_exp_f32_e32 v136, v193
	v_exp_f32_e32 v137, v195
	v_pk_add_f32 v[48:49], v[128:129], v[48:49]
	v_sub_f32_e32 v197, v62, v15
	v_sub_f32_e32 v199, v63, v15
	v_exp_f32_e32 v134, v194
	v_exp_f32_e32 v135, v196
	v_pk_add_f32 v[48:49], v[126:127], v[48:49]
	v_sub_f32_e32 v198, v78, v15
	v_sub_f32_e32 v200, v79, v15
	v_exp_f32_e32 v140, v197
	v_exp_f32_e32 v141, v199
	v_pk_add_f32 v[48:49], v[132:133], v[48:49]
	v_exp_f32_e32 v138, v198
	v_exp_f32_e32 v139, v200
	v_pk_add_f32 v[48:49], v[130:131], v[48:49]
	v_mov_b64_e32 v[78:79], v[46:47]
	v_pk_add_f32 v[48:49], v[136:137], v[48:49]
	v_mov_b64_e32 v[76:77], v[44:45]
	v_pk_add_f32 v[48:49], v[134:135], v[48:49]
	v_mov_b64_e32 v[74:75], v[42:43]
	v_pk_add_f32 v[48:49], v[140:141], v[48:49]
	v_mov_b64_e32 v[72:73], v[40:41]
	v_pk_add_f32 v[48:49], v[138:139], v[48:49]
	v_mov_b64_e32 v[70:71], v[38:39]
	v_add_f32_e32 v117, v48, v49
	v_mov_b64_e32 v[62:63], v[30:31]
	v_cmp_nge_f32_e32 vcc, s0, v117
	v_mov_b64_e32 v[68:69], v[36:37]
	v_mov_b64_e32 v[66:67], v[34:35]
	v_mov_b64_e32 v[64:65], v[32:33]
	v_mov_b64_e32 v[60:61], v[28:29]
	v_mov_b64_e32 v[58:59], v[26:27]
	v_mov_b64_e32 v[56:57], v[24:25]
	v_mov_b64_e32 v[54:55], v[22:23]
	v_mov_b64_e32 v[52:53], v[20:21]
	v_mov_b64_e32 v[50:51], v[18:19]
	v_mov_b64_e32 v[48:49], v[16:17]
	s_cbranch_vccnz .Lna_slow1

.Lna_slow1:
	v_max_f32_e32 v10, v172, v172
	v_max_f32_e32 v11, v171, v171
	v_max_f32_e32 v10, v11, v10
	v_max_f32_e32 v11, v174, v174
	v_max_f32_e32 v12, v173, v173
	v_max_f32_e32 v11, v12, v11
	v_max_f32_e32 v12, v176, v176
	v_max_f32_e32 v13, v175, v175
	v_max3_f32 v10, v169, v170, v10
	v_max_f32_e32 v12, v13, v12
	v_max3_f32 v10, v10, v11, v12
	v_max_f32_e32 v11, v178, v178
	v_max_f32_e32 v12, v177, v177
	v_max_f32_e32 v11, v12, v11
	v_max_f32_e32 v12, v180, v180
	v_max_f32_e32 v13, v179, v179
	v_max_f32_e32 v12, v13, v12
	v_max3_f32 v10, v10, v11, v12
	v_max_f32_e32 v11, v182, v182
	v_max_f32_e32 v12, v181, v181
	v_max_f32_e32 v11, v12, v11
	v_max_f32_e32 v12, v184, v184
	v_max_f32_e32 v13, v183, v183
	v_max_f32_e32 v12, v13, v12
	v_max3_f32 v10, v10, v11, v12
	v_max_f32_e32 v11, v186, v186
	v_max_f32_e32 v12, v185, v185
	v_max_f32_e32 v11, v12, v11
	v_max_f32_e32 v12, v188, v188
	v_max_f32_e32 v13, v187, v187
	v_max_f32_e32 v12, v13, v12
	v_max3_f32 v10, v10, v11, v12
	v_max_f32_e32 v11, v190, v190
	v_max_f32_e32 v12, v189, v189
	v_max_f32_e32 v11, v12, v11
	v_max_f32_e32 v12, v192, v192
	v_max_f32_e32 v13, v191, v191
	v_max_f32_e32 v12, v13, v12
	v_max3_f32 v10, v10, v11, v12
	v_max_f32_e32 v11, v194, v194
	v_max_f32_e32 v12, v193, v193
	v_max_f32_e32 v11, v12, v11
	v_max_f32_e32 v12, v196, v196
	v_max_f32_e32 v13, v195, v195
	v_max_f32_e32 v12, v13, v12
	v_max3_f32 v10, v10, v11, v12
	v_max_f32_e32 v11, v198, v198
	v_max_f32_e32 v12, v197, v197
	v_max_f32_e32 v11, v12, v11
	v_max_f32_e32 v12, v200, v200
	v_max_f32_e32 v13, v199, v199
	v_max_f32_e32 v12, v13, v12
	v_max3_f32 v10, v10, v11, v12
	v_and_b32_e32 v12, 64, v220
	v_xor_b32_e32 v11, 32, v220
	v_add_u32_e32 v12, 64, v12
	v_cmp_lt_i32_e32 vcc, v11, v12
	s_nop 1
	v_cndmask_b32_e32 v11, v220, v11, vcc
	v_lshlrev_b32_e32 v11, 2, v11
	ds_bpermute_b32 v11, v11, v10
	s_waitcnt lgkmcnt(0)
	v_max3_f32 v116, v10, v11, 0
	v_exp_f32_e64 v10, -v116
	v_sub_f32_e32 v13, v171, v116
	v_sub_f32_e32 v104, v172, v116
	v_exp_f32_e32 v13, v13
	v_mul_f32_e32 v167, v151, v10
	v_pk_mul_f32 v[62:63], v[30:31], v[10:11] op_sel_hi:[1,0]
	v_pk_mul_f32 v[60:61], v[28:29], v[10:11] op_sel_hi:[1,0]
	v_pk_mul_f32 v[58:59], v[26:27], v[10:11] op_sel_hi:[1,0]
	v_pk_mul_f32 v[56:57], v[24:25], v[10:11] op_sel_hi:[1,0]
	v_pk_mul_f32 v[54:55], v[22:23], v[10:11] op_sel_hi:[1,0]
	v_pk_mul_f32 v[52:53], v[20:21], v[10:11] op_sel_hi:[1,0]
	v_pk_mul_f32 v[50:51], v[18:19], v[10:11] op_sel_hi:[1,0]
	v_pk_mul_f32 v[48:49], v[16:17], v[10:11] op_sel_hi:[1,0]
	v_pk_mul_f32 v[78:79], v[46:47], v[10:11] op_sel_hi:[1,0]
	v_pk_mul_f32 v[76:77], v[44:45], v[10:11] op_sel_hi:[1,0]
	v_pk_mul_f32 v[74:75], v[42:43], v[10:11] op_sel_hi:[1,0]
	v_pk_mul_f32 v[72:73], v[40:41], v[10:11] op_sel_hi:[1,0]
	v_pk_mul_f32 v[70:71], v[38:39], v[10:11] op_sel_hi:[1,0]
	v_pk_mul_f32 v[68:69], v[36:37], v[10:11] op_sel_hi:[1,0]
	v_pk_mul_f32 v[66:67], v[34:35], v[10:11] op_sel_hi:[1,0]
	v_pk_mul_f32 v[64:65], v[32:33], v[10:11] op_sel_hi:[1,0]
	v_sub_f32_e32 v10, v169, v116
	v_sub_f32_e32 v11, v170, v116
	v_exp_f32_e32 v12, v10
	v_sub_f32_e32 v105, v173, v116
	v_sub_f32_e32 v107, v175, v116
	v_exp_f32_e32 v10, v11
	v_exp_f32_e32 v11, v104
	v_sub_f32_e32 v117, v174, v116
	v_sub_f32_e32 v118, v176, v116
	v_exp_f32_e32 v106, v105
	v_exp_f32_e32 v107, v107
	v_exp_f32_e32 v104, v117
	v_exp_f32_e32 v105, v118
	v_pk_add_f32 v[118:119], v[12:13], 0 op_sel_hi:[1,0]
	v_sub_f32_e32 v120, v177, v116
	v_sub_f32_e32 v121, v179, v116
	v_pk_add_f32 v[118:119], v[10:11], v[118:119]
	v_sub_f32_e32 v122, v178, v116
	v_sub_f32_e32 v123, v180, v116
	v_pk_add_f32 v[118:119], v[118:119], v[106:107]
	v_exp_f32_e32 v120, v120
	v_exp_f32_e32 v121, v121
	v_sub_f32_e32 v124, v181, v116
	v_sub_f32_e32 v125, v183, v116
	v_pk_add_f32 v[126:127], v[104:105], v[118:119]
	v_exp_f32_e32 v118, v122
	v_exp_f32_e32 v119, v123
	v_sub_f32_e32 v128, v182, v116
	v_sub_f32_e32 v129, v184, v116
	v_exp_f32_e32 v124, v124
	v_exp_f32_e32 v125, v125
	v_exp_f32_e32 v122, v128
	v_exp_f32_e32 v123, v129
	v_pk_add_f32 v[126:127], v[126:127], v[120:121]
	v_sub_f32_e32 v130, v185, v116
	v_sub_f32_e32 v132, v187, v116
	v_pk_add_f32 v[126:127], v[118:119], v[126:127]
	v_sub_f32_e32 v131, v186, v116
	v_sub_f32_e32 v133, v188, v116
	v_pk_add_f32 v[126:127], v[126:127], v[124:125]
	v_exp_f32_e32 v128, v130
	v_exp_f32_e32 v129, v132
	v_sub_f32_e32 v136, v189, v116
	v_sub_f32_e32 v138, v191, v116
	v_pk_add_f32 v[134:135], v[122:123], v[126:127]
	v_exp_f32_e32 v126, v131
	v_exp_f32_e32 v127, v133
	v_sub_f32_e32 v137, v190, v116
	v_sub_f32_e32 v139, v192, v116
	v_exp_f32_e32 v132, v136
	v_exp_f32_e32 v133, v138
	v_exp_f32_e32 v130, v137
	v_exp_f32_e32 v131, v139
	v_pk_add_f32 v[134:135], v[134:135], v[128:129]
	v_sub_f32_e32 v140, v193, v116
	v_sub_f32_e32 v169, v195, v116
	v_pk_add_f32 v[134:135], v[126:127], v[134:135]
	v_sub_f32_e32 v141, v194, v116
	v_sub_f32_e32 v172, v196, v116
	v_pk_add_f32 v[134:135], v[134:135], v[132:133]
	v_exp_f32_e32 v136, v140
	v_exp_f32_e32 v137, v169
	v_sub_f32_e32 v173, v197, v116
	v_sub_f32_e32 v175, v199, v116
	v_pk_add_f32 v[170:171], v[130:131], v[134:135]
	v_exp_f32_e32 v134, v141
	v_exp_f32_e32 v135, v172
	v_sub_f32_e32 v174, v198, v116
	v_sub_f32_e32 v176, v200, v116
	v_exp_f32_e32 v140, v173
	v_exp_f32_e32 v141, v175
	v_exp_f32_e32 v138, v174
	v_exp_f32_e32 v139, v176
	v_pk_add_f32 v[170:171], v[170:171], v[136:137]
	v_mov_b32_e32 v172, v15
	v_pk_add_f32 v[170:171], v[134:135], v[170:171]
	s_nop 0
	v_pk_add_f32 v[170:171], v[170:171], v[140:141]
	s_nop 0
	v_pk_add_f32 v[170:171], v[138:139], v[170:171]
	s_nop 0
	v_mov_b32_e32 v173, v170
	v_mov_b32_e32 v117, v171
	v_pk_add_f32 v[116:117], v[172:173], v[116:117]
	s_branch .LBB0_179

.Ldl_ctxaddr:
	s_sub_i32 s20, s3, 63
	s_lshl_b64 s[4:5], s[20:21], 15
	v_lshl_add_u64 v[66:67], v[172:173], 0, s[4:5]
	s_branch .LBB0_232
	s_nop 0
	s_nop 0
	s_nop 0
	s_nop 0
	s_nop 0
	s_nop 0
	s_nop 0
	s_nop 0
	s_nop 0
	s_nop 0
	s_nop 0
	s_nop 0
	s_nop 0
	s_nop 0
	s_nop 0
	s_nop 0
	s_nop 0
.LBB0_229:
	v_mov_b64_e32 v[174:175], v[182:183]
	s_cmpk_lg_i32 s3, 0x43
	s_cselect_b64 s[0:1], -1, 0
	s_cmpk_eq_i32 s3, 0x43
	s_cbranch_scc1 .LBB0_233
